# grid barrier between decode-combine and out-projection replaced by a completion counter that only the sample-row workgroups wait on (measure 1)
# baseline (speedup 1.0000x reference)
; #define PSTAMP(i) do { if (PROBE_SEG >= 20 && blockIdx.x == PROBE_BLK && threadIdx.x == 0) ((volatile LAS unsigned long long*)(ctlw + 32))[8 + (i)] = __builtin_amdgcn_s_memrealtime(); } while (0)
; #define QUEUE_LOOP(qi, total, ...) for (;;) { __syncthreads(); if (threadIdx.x == 0) ctlw[16] = __hip_atomic_fetch_add(qbase + 64 * (qi), 1u, __ATOMIC_RELAXED, __HIP_MEMORY_SCOPE_AGENT); \
;         __syncthreads(); const int u = (int)ctlw[16]; if (u >= (total)) break; __VA_ARGS__ }
; __device__ __forceinline__ void phase4(const Params& p, LAS unsigned char* lds, volatile LAS unsigned* ctlw, int vcu, int G, int qset) {
;     ...
;     PSTAMP(0);
;     QUEUE_LOOP(5, NBATCH * 16 * 8, { const int v = NBATCH * 16 * 8 - 1 - u;
;         ssd_out_unit<false>(p.ws, p.out, p.in[I_ALOG], p.in[I_DSKIP], p.in[I_SSDNW], p.in[I_SSM], p.in[I_SCONV], p.in[I_CONVW], p.in[I_CONVB], lds, (v >> 3) & 3, v >> 5, v & 7); })
.LBB0_1074:
	s_cmp_eq_u32 s98, 4
	s_cbranch_scc1 .Lp4_done
	s_add_u32 s6, s90, 0x14e00000
	s_addc_u32 s7, s91, 0
	s_add_u32 s8, s90, 0xd200000
	s_addc_u32 s9, s91, 0
	s_add_u32 s10, s88, 0x8080000
	s_addc_u32 s11, s89, 0
	s_add_u32 s12, s90, 0x13c00000
	s_addc_u32 s13, s91, 0
	s_add_u32 s14, s90, 0xdd00000
	s_addc_u32 s15, s91, 0
	s_add_u32 s24, s90, 0xe000000
	s_addc_u32 s28, s91, 0
	s_add_u32 s16, s90, 0x16200004
	s_addc_u32 s17, s91, 0
	s_add_i32 s29, 0, 0x27e40
	s_waitcnt vmcnt(0)
	v_mbcnt_hi_u32_b32 v75, -1, v190
	v_bfrev_b32_e32 v2, 0.5
	s_mov_b32 s5, 0
	v_cmp_eq_u32_e64 s[0:1], 0, v0
	v_mov_b32_e32 v51, 0
	v_mov_b32_e32 v1, s29
	s_movk_i32 s30, 0x1ff
	s_add_i32 s31, 0, 0x1e000
	s_movk_i32 s33, 0x100
	s_add_i32 s34, 0, 0x1e200
	s_add_i32 s35, 0, 0x1e1fc
	s_movk_i32 s40, 0x2000
	s_movk_i32 s41, 0x4000
	s_add_i32 s42, 0, 0x1e404
	s_add_i32 s43, 0, 0x1e408
	s_movk_i32 s44, 0x80
	s_add_i32 s45, 0, 0x1e40c
	s_add_i32 s46, 0, 0x1e410
	s_add_i32 s47, 0, 0x1e414
	s_add_i32 s48, 0, 0x1e418
	s_add_i32 s49, 0, 0x1e41c
	s_add_i32 s50, 0, 0x1e420
	s_add_i32 s51, 0, 0x1e424
	s_add_i32 s52, 0, 0x1e428
	s_add_i32 s53, 0, 0x1e42c
	s_add_i32 s54, 0, 0x1e430
	s_add_i32 s55, 0, 0x1e434
	s_add_i32 s62, 0, 0x1e438
	s_add_i32 s63, 0, 0x1e43c
	s_add_i32 s64, 0, 0x15400
	s_movk_i32 s65, 0x110
	s_add_i32 s66, 0, 0x19800
	s_movk_i32 s67, 0x90
	s_add_i32 s68, 0, 0x11000
	s_movk_i32 s69, 0x3600
	s_mov_b64 s[18:19], 0x5a02000
	v_and_b32_e32 v77, 64, v75
	v_add_u32_e32 v79, -1, v75
	v_add_u32_e32 v80, -2, v75
	v_add_u32_e32 v81, -4, v75
	v_add_u32_e32 v82, -8, v75
	v_add_u32_e32 v83, -16, v75
	v_subrev_u32_e32 v84, 32, v75
	v_lshl_or_b32 v85, v75, 2, v2
	s_branch .LBB0_1077

; #define PSTAMP(i) do { if (PROBE_SEG >= 20 && blockIdx.x == PROBE_BLK && threadIdx.x == 0) ((volatile LAS unsigned long long*)(ctlw + 32))[8 + (i)] = __builtin_amdgcn_s_memrealtime(); } while (0)
; #define QUEUE_LOOP(qi, total, ...) for (;;) { __syncthreads(); if (threadIdx.x == 0) ctlw[16] = __hip_atomic_fetch_add(qbase + 64 * (qi), 1u, __ATOMIC_RELAXED, __HIP_MEMORY_SCOPE_AGENT); \
;         __syncthreads(); const int u = (int)ctlw[16]; if (u >= (total)) break; __VA_ARGS__ }
; __device__ __forceinline__ void phase4(const Params& p, LAS unsigned char* lds, volatile LAS unsigned* ctlw, int vcu, int G, int qset) {
;     ...
;     for (int u = G - 1 - (int)blockIdx.x; u < DSEQ * 8; u += G) {
;         const int seq = u >> 3, head = u & 7, i = wave;
;     ...
;     }
;     PSTAMP(3);
;     PSTAMP(0);
;     QUEUE_LOOP(5, NBATCH * 16 * 8, { const int v = NBATCH * 16 * 8 - 1 - u;
;         ssd_out_unit<false>(p.ws, p.out, p.in[I_ALOG], p.in[I_DSKIP], p.in[I_SSDNW], p.in[I_SSM], p.in[I_SCONV], p.in[I_CONVW], p.in[I_CONVB], lds, (v >> 3) & 3, v >> 5, v & 7); })
;     PSTAMP(1);
.Lp4_done:
	v_readlane_b32 s4, v254, 2
	s_sub_i32 s4, s4, 64
	s_cmp_lt_i32 s95, s4
	s_cbranch_scc1 .Lp4_go
	s_waitcnt vmcnt(0) lgkmcnt(0)
	s_barrier
	v_cmp_eq_u32_e32 vcc, 0, v0
	s_and_saveexec_b64 s[4:5], vcc
	s_cbranch_execz .Lp4_pub_done
	buffer_wbl2 sc1
	s_waitcnt vmcnt(0)
	v_mov_b32_e32 v1, 0xb00
	v_mov_b32_e32 v2, 1
	global_atomic_add v1, v2, s[90:91]
	s_waitcnt vmcnt(0)

; #define STAMP() do { if (PROBE_SEG >= 0 && bx == 0 && tid == 0) { tst[nst] = __builtin_amdgcn_s_memrealtime(); } ++nst; } while (0)
; #define BOTH(k) (IN(k) && IN((k) + 1))
; __global__ void __launch_bounds__(512, 2) hymba_fwd(Params p) {
;     ...
;     if (IN(4)) { phase4(p, lds, ctlw, vcu, G, 0); if (BOTH(4)) GBAR(); STAMP(); }
;     if (IN(5)) {
.Lp4_go:
	v_readlane_b32 s50, v254, 3
	v_readlane_b32 s51, v254, 4
	s_branch .LBB0_1184

; #define LAS __attribute__((address_space(3)))
; #define PSTAMP0(i) do { if (PROBE_SEG >= 40 && blockIdx.x == 0 && threadIdx.x == 0) ((volatile LAS unsigned long long*)(ctlw + 32))[20 + (i)] = __builtin_amdgcn_s_memrealtime(); } while (0)
; __device__ __forceinline__ void sample_outproj(const Params& p, LAS unsigned char* lds, int c) {
;     int tid = threadIdx.x; asm volatile("" : "+v"(tid));
;     const int wid = __builtin_amdgcn_readfirstlane(tid >> 6), lane = tid & 63, j16 = lane & 15, ig = lane >> 4;
;     const bf16_t* MIX = (const bf16_t*)(p.ws + WS_MIX) + (size_t)MP * 2048; const bf16_t* WT = (const bf16_t*)(p.ws + WS_WOUT) + (size_t)(16 * c) * 2048;
;     const float* SSQ = (const float*)(p.ws + WS_SSQ) + (size_t)MP * 8;
;     f32x4 acc[4];
; #pragma unroll
;     for (int rb = 0; rb < 4; ++rb) acc[rb] = f32x4{0.f, 0.f, 0.f, 0.f};
;     float xin[2];
; #pragma unroll
;     for (int i = 0; i < 2; ++i) { const int e = tid + 512 * i; xin[i] = p.in[I_XS][(size_t)(e >> 4) * DM + 16 * c + (e & 15)]; }
;     LAS float* rsl = (LAS float*)(lds + 32768);
;     f32x4 sq0 = f32x4{0.f, 0.f, 0.f, 0.f}, sq1 = sq0;
;     if (tid < 64) { sq0 = *(const f32x4*)(SSQ + tid * 8); sq1 = *(const f32x4*)(SSQ + tid * 8 + 4); }
; __global__ void __launch_bounds__(512, 2) hymba_fwd(Params p) {
;     ...
;     if (IN(5)) {
;         pg8::Gemm g{(const bf16_t*)(p.ws + WS_MIX), (const bf16_t*)(p.ws + WS_WOUT), nullptr, nullptr, DM};
;         pg8::Order S; S.init(MP / 256, DM / 256, 0, 1, G, bx);
;         Epi5 E{p.in[I_XP], p.out, (const float*)(p.ws + WS_SSQ)};
;         PSTAMP0(4);
;         if (bx < 128) { sample_outproj(p, lds, bx); __syncthreads(); }
.LBB0_1184:
	s_cmp_gt_i32 s50, 5
	s_cselect_b64 s[0:1], -1, 0
	s_cmp_lt_i32 s51, 6
	s_cselect_b64 s[2:3], -1, 0
	s_or_b64 s[0:1], s[0:1], s[2:3]
	s_and_b64 vcc, exec, s[0:1]
	s_cbranch_vccnz .LBB0_1219
	s_add_u32 s24, s90, 0x2600000
	s_addc_u32 s33, s91, 0
	s_cmpk_gt_i32 s95, 0x7f
	s_cbranch_scc1 .LBB0_1193
	s_mov_b32 s5, 0x8000
	v_mov_b32_e32 v2, 0
.Lcb_poll:
	global_load_dword v1, v2, s[90:91] offset:2816 sc1
	s_waitcnt vmcnt(0)
	v_readfirstlane_b32 s4, v1
	s_cmpk_gt_u32 s4, 63
	s_cbranch_scc1 .Lcb_done
	s_add_i32 s5, s5, -1
	s_cmp_eq_u32 s5, 0
	s_cbranch_scc1 .Lcb_done
	s_sleep 8
	s_branch .Lcb_poll
.Lcb_done:
	buffer_inv sc1
	s_waitcnt vmcnt(0)
	s_lshl_b32 s4, s95, 4
	s_ashr_i32 s5, s4, 31
	s_waitcnt vmcnt(0)
	v_mov_b32_e32 v33, v0
	s_lshl_b64 s[2:3], s[4:5], 2
	v_mov_b32_e32 v11, 0
	v_and_b32_e32 v10, 15, v33
	s_add_u32 s0, s38, s2
	v_ashrrev_i32_e32 v4, 4, v33
	v_add_u32_e32 v32, 0x200, v33
	s_addc_u32 s1, s39, s3
	v_lshlrev_b32_e32 v26, 2, v10
	v_mov_b32_e32 v27, v11
	v_ashrrev_i32_e32 v5, 31, v4
	v_ashrrev_i32_e32 v6, 4, v32
	s_waitcnt lgkmcnt(0)
	v_lshl_add_u64 v[2:3], s[0:1], 0, v[26:27]
	v_lshlrev_b64 v[30:31], 13, v[4:5]
	v_ashrrev_i32_e32 v7, 31, v6
	v_lshl_add_u64 v[4:5], v[2:3], 0, v[30:31]
	v_lshlrev_b64 v[28:29], 13, v[6:7]
	v_lshl_add_u64 v[2:3], v[2:3], 0, v[28:29]
	global_load_dword v27, v[4:5], off
	global_load_dword v1, v[2:3], off
	v_readfirstlane_b32 s8, v33
	v_cmp_gt_i32_e64 s[0:1], 64, v33
	v_mov_b32_e32 v6, 0
	v_mov_b32_e32 v7, 0
	v_mov_b32_e32 v8, 0
	v_mov_b32_e32 v9, 0
	v_mov_b32_e32 v2, 0
	v_mov_b32_e32 v3, 0
	v_mov_b32_e32 v4, 0
	v_mov_b32_e32 v5, 0
	s_and_saveexec_b64 s[6:7], s[0:1]
	s_cbranch_execz .LBB0_1188
	v_lshlrev_b32_e32 v2, 3, v33
	v_ashrrev_i32_e32 v3, 31, v2
	v_lshl_add_u64 v[2:3], v[2:3], 2, s[90:91]
	v_add_co_u32_e32 v14, vcc, 0xdd40000, v2
	s_mov_b64 s[10:11], 0xdd40000
	s_nop 0
	v_addc_co_u32_e32 v15, vcc, 0, v3, vcc
	v_lshl_add_u64 v[12:13], v[2:3], 0, s[10:11]
	global_load_dwordx4 v[2:5], v[14:15], off
	global_load_dwordx4 v[6:9], v[12:13], off offset:16
